# v18: stick-breaking softplus overflow guard as a clamp of z at 126 (v_min) instead of compare+select at 30; same f32 results
# speedup vs baseline: 1.0973x; 1.0104x over previous
; #define LAS __attribute__((address_space(3)))
; #define MFMA32(a, b, c) __builtin_amdgcn_mfma_f32_32x32x16_bf16((a), (b), (c), 0, 0, 0)
; DI int crow(int r, int hi) { return (r & 3) + 8 * (r >> 2) + 4 * hi; }
; DI float ex2(float x) { return __builtin_amdgcn_exp2f(x); }
; DI float lg2(float x) { return __builtin_amdgcn_logf(x); }
; DI void sb_unit(LAS char* lds, int b, int h, int qb, const bf16_t* __restrict__ Q, const bf16_t* __restrict__ K, const bf16_t* __restrict__ VT, const bf16_t* __restrict__ G, bf16_t* __restrict__ MIX) {
;     ...
;         const LAS char* Kt = lds + (it & 1) * 16384; const LAS char* Vt = Kt + 8192;
;         const int kv0 = 64 * T;
;         if (kv0 < qw0 + 31 && !done) {
;             f32x16 p0 = splat16(0.f), p1 = splat16(0.f);
; #pragma unroll
;             for (int d0 = 0; d0 < 4; ++d0) { const bf16x8 k0 = ldsv(Kt + off128(r32, 2 * d0 + hi)), k1 = ldsv(Kt + off128(32 + r32, 2 * d0 + hi)); p0 = MFMA32(k0, qf[d0], p0); p1 = MFMA32(k1, qf[d0], p1); }
;             const bool diag = (kv0 + 63 >= qw0);
;             f32x16 L0, L1;
; #pragma unroll
;             for (int r = 0; r < 16; ++r) {
;                 { const float z = p0[r]; const float lg = (z > 30.f) ? z : lg2(1.0f + ex2(z)); const bool valid = !diag || (kv0 + crow(r, hi) < tq); L0[r] = valid ? -lg : 0.f; p0[r] = valid ? (z - lg) : -1e30f; }
.LBB0_422:
	s_and_b32 s42, s38, 1
	s_cmp_lt_i32 s39, 0
	s_cbranch_scc1 .LBB0_424
	s_cmp_ge_i32 s39, s26
	s_cselect_b64 s[0:1], -1, 0
	v_cmp_ne_u32_e32 vcc, 0, v36
	s_or_b64 s[0:1], s[0:1], vcc
	s_and_b64 vcc, exec, s[0:1]
	s_cbranch_vccnz .LBB0_424
	s_lshr_b32 s0, s39, 6
	s_and_b32 s0, s0, 7
	s_lshl_b32 s0, s0, 14
	s_add_i32 s43, s0, 0
	v_add_u32_e32 v35, s43, v103
	v_add_u32_e32 v40, v35, v104
	ds_read_b128 v[36:39], v40
	ds_read_b128 v[40:43], v40 offset:4096
	v_add_u32_e32 v112, v35, v105
	ds_read_b128 v[108:111], v112
	ds_read_b128 v[112:115], v112 offset:4096
	s_add_i32 s0, s39, 63
	s_waitcnt lgkmcnt(3)
	v_mfma_f32_32x32x16_bf16 v[52:67], v[36:39], v[68:71], 0
	s_cmp_lt_i32 s0, s24
	s_cselect_b64 s[0:1], -1, 0
	v_readlane_b32 s4, v254, 48
	v_readlane_b32 s6, v254, 50
	v_readlane_b32 s7, v254, 51
	v_readlane_b32 s5, v254, 49
	s_mov_b32 s6, s4
	s_waitcnt lgkmcnt(2)
	v_mfma_f32_32x32x16_bf16 v[36:51], v[40:43], v[68:71], 0
	s_mov_b32 s7, s4
	s_mov_b32 s5, s4
	s_waitcnt lgkmcnt(1)
	v_mfma_f32_32x32x16_bf16 v[52:67], v[108:111], v[72:75], v[52:67]
	s_waitcnt lgkmcnt(0)
	v_mfma_f32_32x32x16_bf16 v[36:51], v[112:115], v[72:75], v[36:51]
	v_add_u32_e32 v112, v35, v106
	ds_read_b128 v[108:111], v112
	ds_read_b128 v[112:115], v112 offset:4096
	v_add_u32_e32 v35, v35, v107
	s_waitcnt lgkmcnt(1)
	v_mfma_f32_32x32x16_bf16 v[52:67], v[108:111], v[76:79], v[52:67]
	s_waitcnt lgkmcnt(0)
	v_mfma_f32_32x32x16_bf16 v[36:51], v[112:115], v[76:79], v[36:51]
	ds_read_b128 v[108:111], v35
	ds_read_b128 v[112:115], v35 offset:4096
	v_add_u32_e32 v35, s39, v102
	v_add_u32_e32 v133, 24, v35
	v_add_u32_e32 v138, 58, v35
	s_waitcnt lgkmcnt(1)
	v_mfma_f32_32x32x16_bf16 v[52:67], v[108:111], v[80:83], v[52:67]
	v_add_u32_e32 v110, 32, v35
	s_waitcnt lgkmcnt(0)
	v_mfma_f32_32x32x16_bf16 v[36:51], v[112:115], v[80:83], v[36:51]
	s_nop 8
	v_min_f32_e32 v52, 0x42fc0000, v52
	v_min_f32_e32 v53, 0x42fc0000, v53
	v_min_f32_e32 v54, 0x42fc0000, v54
	v_min_f32_e32 v55, 0x42fc0000, v55
	v_min_f32_e32 v56, 0x42fc0000, v56
	v_min_f32_e32 v57, 0x42fc0000, v57
	v_min_f32_e32 v58, 0x42fc0000, v58
	v_min_f32_e32 v59, 0x42fc0000, v59
	v_min_f32_e32 v60, 0x42fc0000, v60
	v_min_f32_e32 v61, 0x42fc0000, v61
	v_min_f32_e32 v62, 0x42fc0000, v62
	v_min_f32_e32 v63, 0x42fc0000, v63
	v_min_f32_e32 v64, 0x42fc0000, v64
	v_min_f32_e32 v65, 0x42fc0000, v65
	v_min_f32_e32 v66, 0x42fc0000, v66
	v_min_f32_e32 v67, 0x42fc0000, v67
	v_min_f32_e32 v36, 0x42fc0000, v36
	v_min_f32_e32 v37, 0x42fc0000, v37
	v_min_f32_e32 v38, 0x42fc0000, v38
	v_min_f32_e32 v39, 0x42fc0000, v39
	v_min_f32_e32 v40, 0x42fc0000, v40
	v_min_f32_e32 v41, 0x42fc0000, v41
	v_min_f32_e32 v42, 0x42fc0000, v42
	v_min_f32_e32 v43, 0x42fc0000, v43
	v_min_f32_e32 v44, 0x42fc0000, v44
	v_min_f32_e32 v45, 0x42fc0000, v45
	v_min_f32_e32 v46, 0x42fc0000, v46
	v_min_f32_e32 v47, 0x42fc0000, v47
	v_min_f32_e32 v48, 0x42fc0000, v48
	v_min_f32_e32 v49, 0x42fc0000, v49
	v_min_f32_e32 v50, 0x42fc0000, v50
	v_min_f32_e32 v51, 0x42fc0000, v51
	v_exp_f32_e32 v160, v52
	v_exp_f32_e32 v161, v53
	v_exp_f32_e32 v162, v54
	v_exp_f32_e32 v163, v55
	v_exp_f32_e32 v164, v56
	v_exp_f32_e32 v165, v57
	v_exp_f32_e32 v166, v58
	v_exp_f32_e32 v167, v59
	v_exp_f32_e32 v168, v60
	v_exp_f32_e32 v169, v61
	v_exp_f32_e32 v170, v62
	v_exp_f32_e32 v171, v63
	v_exp_f32_e32 v172, v64
	v_exp_f32_e32 v173, v65
	v_exp_f32_e32 v174, v66
	v_exp_f32_e32 v175, v67
	v_exp_f32_e32 v176, v36
	v_exp_f32_e32 v177, v37
	v_exp_f32_e32 v178, v38
	v_exp_f32_e32 v179, v39
	v_exp_f32_e32 v180, v40
	v_exp_f32_e32 v181, v41
	v_exp_f32_e32 v182, v42
	v_exp_f32_e32 v183, v43
	v_exp_f32_e32 v184, v44
	v_exp_f32_e32 v185, v45
	v_exp_f32_e32 v186, v46
	v_exp_f32_e32 v187, v47
	v_exp_f32_e32 v188, v48
	v_exp_f32_e32 v189, v49
	v_exp_f32_e32 v190, v50
	v_exp_f32_e32 v191, v51
	v_add_f32_e32 v160, 1.0, v160
	v_add_f32_e32 v161, 1.0, v161
	v_add_f32_e32 v162, 1.0, v162
	v_add_f32_e32 v163, 1.0, v163
	v_add_f32_e32 v164, 1.0, v164
	v_add_f32_e32 v165, 1.0, v165
	v_add_f32_e32 v166, 1.0, v166
	v_add_f32_e32 v167, 1.0, v167
	v_add_f32_e32 v168, 1.0, v168
	v_add_f32_e32 v169, 1.0, v169
	v_add_f32_e32 v170, 1.0, v170
	v_add_f32_e32 v171, 1.0, v171
	v_add_f32_e32 v172, 1.0, v172
	v_add_f32_e32 v173, 1.0, v173
	v_add_f32_e32 v174, 1.0, v174
	v_add_f32_e32 v175, 1.0, v175
	v_add_f32_e32 v176, 1.0, v176
	v_add_f32_e32 v177, 1.0, v177
	v_add_f32_e32 v178, 1.0, v178
	v_add_f32_e32 v179, 1.0, v179
	v_add_f32_e32 v180, 1.0, v180
	v_add_f32_e32 v181, 1.0, v181
	v_add_f32_e32 v182, 1.0, v182
	v_add_f32_e32 v183, 1.0, v183
	v_add_f32_e32 v184, 1.0, v184
	v_add_f32_e32 v185, 1.0, v185
	v_add_f32_e32 v186, 1.0, v186
	v_add_f32_e32 v187, 1.0, v187
	v_add_f32_e32 v188, 1.0, v188
	v_add_f32_e32 v189, 1.0, v189
	v_add_f32_e32 v190, 1.0, v190
	v_add_f32_e32 v191, 1.0, v191
	v_log_f32_e32 v160, v160
	v_log_f32_e32 v161, v161
	v_log_f32_e32 v162, v162
	v_log_f32_e32 v163, v163
	v_log_f32_e32 v164, v164
	v_log_f32_e32 v165, v165
	v_log_f32_e32 v166, v166
	v_log_f32_e32 v167, v167
	v_log_f32_e32 v168, v168
	v_log_f32_e32 v169, v169
	v_log_f32_e32 v170, v170
	v_log_f32_e32 v171, v171
	v_log_f32_e32 v172, v172
	v_log_f32_e32 v173, v173
	v_log_f32_e32 v174, v174
	v_log_f32_e32 v175, v175
	v_log_f32_e32 v176, v176
	v_log_f32_e32 v177, v177
	v_log_f32_e32 v178, v178
	v_log_f32_e32 v179, v179
	v_log_f32_e32 v180, v180
	v_log_f32_e32 v181, v181
	v_log_f32_e32 v182, v182
	v_log_f32_e32 v183, v183
	v_log_f32_e32 v184, v184
	v_log_f32_e32 v185, v185
	v_log_f32_e32 v186, v186
	v_log_f32_e32 v187, v187
	v_log_f32_e32 v188, v188
	v_log_f32_e32 v189, v189
	v_log_f32_e32 v190, v190
	v_log_f32_e32 v191, v191
	s_and_b64 vcc, exec, s[0:1]
	s_cbranch_vccz .Lsb_sp_diag
; DI int crow(int r, int hi) { return (r & 3) + 8 * (r >> 2) + 4 * hi; }
; DI float ex2(float x) { return __builtin_amdgcn_exp2f(x); }
; DI float lg2(float x) { return __builtin_amdgcn_logf(x); }
; template <int S> DI bf16x8 pack8(const f32x16& x) { u32x4 p; p[0] = cvtpk(x[8 * S], x[8 * S + 1]); p[1] = cvtpk(x[8 * S + 2], x[8 * S + 3]); p[2] = cvtpk(x[8 * S + 4], x[8 * S + 5]); p[3] = cvtpk(x[8 * S + 6], x[8 * S + 7]); return __builtin_bit_cast(bf16x8, p); }
; DI void sb_unit(LAS char* lds, int b, int h, int qb, const bf16_t* __restrict__ Q, const bf16_t* __restrict__ K, const bf16_t* __restrict__ VT, const bf16_t* __restrict__ G, bf16_t* __restrict__ MIX) {
;     ...
;                 { const float z = p0[r]; const float lg = (z > 30.f) ? z : lg2(1.0f + ex2(z)); const bool valid = !diag || (kv0 + crow(r, hi) < tq); L0[r] = valid ? -lg : 0.f; p0[r] = valid ? (z - lg) : -1e30f; }
;                 { const float z = p1[r]; const float lg = (z > 30.f) ? z : lg2(1.0f + ex2(z)); const bool valid = !diag || (kv0 + 32 + crow(r, hi) < tq); L1[r] = valid ? -lg : 0.f; p1[r] = valid ? (z - lg) : -1e30f; }
;             }
;             const bf16x8 Lh0 = pack8<0>(L0), Lh1 = pack8<1>(L0), Lh2 = pack8<0>(L1), Lh3 = pack8<1>(L1);
	v_sub_f32_e32 v109, 0, v160
	v_cvt_pk_bf16_f32 v138, -v160, -v161
	v_cvt_pk_bf16_f32 v139, -v162, -v163
	v_cvt_pk_bf16_f32 v140, -v164, -v165
	v_cvt_pk_bf16_f32 v141, -v166, -v167
	v_cvt_pk_bf16_f32 v142, -v168, -v169
	v_cvt_pk_bf16_f32 v143, -v170, -v171
	v_cvt_pk_bf16_f32 v144, -v172, -v173
	v_cvt_pk_bf16_f32 v145, -v174, -v175
	v_cvt_pk_bf16_f32 v146, -v176, -v177
	v_cvt_pk_bf16_f32 v147, -v178, -v179
	v_cvt_pk_bf16_f32 v148, -v180, -v181
	v_cvt_pk_bf16_f32 v149, -v182, -v183
	v_cvt_pk_bf16_f32 v150, -v184, -v185
	v_cvt_pk_bf16_f32 v151, -v186, -v187
	v_cvt_pk_bf16_f32 v152, -v188, -v189
	v_cvt_pk_bf16_f32 v153, -v190, -v191
	v_sub_f32_e32 v108, v52, v160
	v_sub_f32_e32 v111, v53, v161
	v_sub_f32_e32 v113, v54, v162
	v_sub_f32_e32 v115, v55, v163
	v_sub_f32_e32 v117, v56, v164
	v_sub_f32_e32 v119, v57, v165
	v_sub_f32_e32 v121, v58, v166
	v_sub_f32_e32 v123, v59, v167
	v_sub_f32_e32 v125, v60, v168
	v_sub_f32_e32 v127, v61, v169
	v_sub_f32_e32 v129, v62, v170
	v_sub_f32_e32 v131, v63, v171
	v_sub_f32_e32 v133, v64, v172
	v_sub_f32_e32 v135, v65, v173
	v_sub_f32_e32 v66, v66, v174
	v_sub_f32_e32 v155, v67, v175
	v_sub_f32_e32 v110, v36, v176
	v_sub_f32_e32 v112, v37, v177
	v_sub_f32_e32 v114, v38, v178
	v_sub_f32_e32 v116, v39, v179
	v_sub_f32_e32 v118, v40, v180
	v_sub_f32_e32 v120, v41, v181
	v_sub_f32_e32 v122, v42, v182
	v_sub_f32_e32 v124, v43, v183
	v_sub_f32_e32 v126, v44, v184
	v_sub_f32_e32 v128, v45, v185
	v_sub_f32_e32 v130, v46, v186
	v_sub_f32_e32 v132, v47, v187
	v_sub_f32_e32 v134, v48, v188
	v_sub_f32_e32 v136, v49, v189
	v_sub_f32_e32 v154, v50, v190
	v_sub_f32_e32 v156, v51, v191
	s_branch .Lsb_sp_join
